# PEER u-sweep: rows read at skewed 64-byte chunk offsets per lane (spreads each load instruction over the memory channels), dot products taken from the MFMA diagonal
# speedup vs baseline: 1.0638x; 1.0467x over previous
; __device__ __forceinline__ void ph_peer(const P& p, int l, int nrows, char* smem, int dryc) {
;     ...
;       {
;         const int nit = 8 * n;
;         u32x4 bA[16], bB[16];
;     ...
;         PEER_ULOAD(bA, 0);
; #pragma unroll 1
;         for (int it = 0; it < nit; it += 2) {
;           PEER_ULOAD(bB, it + 1);
;           PEER_UCOMP(bA, it);
;           if (it + 2 < nit) { PEER_ULOAD(bA, it + 2); }
;           PEER_UCOMP(bB, it + 1);
;         }
.LBB0_701:
	v_and_b32_e32 v200, 15, v212
	v_lshrrev_b32_e32 v201, 4, v212
	v_lshlrev_b32_e32 v201, 4, v201
	v_add_u32_e32 v202, 0, v200
	v_and_b32_e32 v202, 15, v202
	v_lshl_or_b32 v176, v202, 6, v201
	v_add_u32_e32 v202, 1, v200
	v_and_b32_e32 v202, 15, v202
	v_lshl_or_b32 v177, v202, 6, v201
	v_add_u32_e32 v202, 2, v200
	v_and_b32_e32 v202, 15, v202
	v_lshl_or_b32 v178, v202, 6, v201
	v_add_u32_e32 v202, 3, v200
	v_and_b32_e32 v202, 15, v202
	v_lshl_or_b32 v179, v202, 6, v201
	v_add_u32_e32 v202, 4, v200
	v_and_b32_e32 v202, 15, v202
	v_lshl_or_b32 v180, v202, 6, v201
	v_add_u32_e32 v202, 5, v200
	v_and_b32_e32 v202, 15, v202
	v_lshl_or_b32 v181, v202, 6, v201
	v_add_u32_e32 v202, 6, v200
	v_and_b32_e32 v202, 15, v202
	v_lshl_or_b32 v182, v202, 6, v201
	v_add_u32_e32 v202, 7, v200
	v_and_b32_e32 v202, 15, v202
	v_lshl_or_b32 v183, v202, 6, v201
	v_add_u32_e32 v202, 8, v200
	v_and_b32_e32 v202, 15, v202
	v_lshl_or_b32 v184, v202, 6, v201
	v_add_u32_e32 v202, 9, v200
	v_and_b32_e32 v202, 15, v202
	v_lshl_or_b32 v185, v202, 6, v201
	v_add_u32_e32 v202, 10, v200
	v_and_b32_e32 v202, 15, v202
	v_lshl_or_b32 v186, v202, 6, v201
	v_add_u32_e32 v202, 11, v200
	v_and_b32_e32 v202, 15, v202
	v_lshl_or_b32 v187, v202, 6, v201
	v_add_u32_e32 v202, 12, v200
	v_and_b32_e32 v202, 15, v202
	v_lshl_or_b32 v188, v202, 6, v201
	v_add_u32_e32 v202, 13, v200
	v_and_b32_e32 v202, 15, v202
	v_lshl_or_b32 v189, v202, 6, v201
	v_add_u32_e32 v202, 14, v200
	v_and_b32_e32 v202, 15, v202
	v_lshl_or_b32 v190, v202, 6, v201
	v_add_u32_e32 v202, 15, v200
	v_and_b32_e32 v202, 15, v202
	v_lshl_or_b32 v191, v202, 6, v201
	v_lshlrev_b32_e32 v225, 2, v200
	v_and_b32_e32 v224, 3, v200
	v_lshrrev_b32_e32 v202, 2, v200
	v_lshl_or_b32 v202, v202, 4, v200
	v_lshlrev_b32_e32 v248, 2, v202
	v_lshrrev_b32_e32 v204, 6, v128
	s_nop 1
	v_readfirstlane_b32 s15, v204
	s_mov_b32 s12, 0
	s_mov_b32 s13, 0
	s_mov_b32 s14, 0
	s_mov_b32 s19, 0
	s_mov_b32 s20, 0
	s_mul_i32 s16, s15, s75
	s_lshl_b32 s15, s15, 2
	s_add_i32 s17, s16, s13
	s_lshl_b32 s17, s17, 9
	s_lshl_b32 s0, s14, 6
	s_add_i32 s17, s17, s0
	v_add_u32_e32 v249, s17, v225
	ds_read_b32 v200, v249
	s_waitcnt lgkmcnt(0)
	v_lshl_or_b32 v202, v200, 10, v176
	global_load_dwordx4 v[0:3], v202, s[58:59]
	v_lshl_or_b32 v203, v200, 10, v177
	global_load_dwordx4 v[4:7], v203, s[58:59]
	v_lshl_or_b32 v202, v200, 10, v178
	global_load_dwordx4 v[8:11], v202, s[58:59]
	v_lshl_or_b32 v203, v200, 10, v179
	global_load_dwordx4 v[12:15], v203, s[58:59]
	v_lshl_or_b32 v202, v200, 10, v180
	global_load_dwordx4 v[16:19], v202, s[58:59]
	v_lshl_or_b32 v203, v200, 10, v181
	global_load_dwordx4 v[20:23], v203, s[58:59]
	v_lshl_or_b32 v202, v200, 10, v182
	global_load_dwordx4 v[24:27], v202, s[58:59]
	v_lshl_or_b32 v203, v200, 10, v183
	global_load_dwordx4 v[28:31], v203, s[58:59]
	v_lshl_or_b32 v202, v200, 10, v184
	global_load_dwordx4 v[32:35], v202, s[58:59]
	v_lshl_or_b32 v203, v200, 10, v185
	global_load_dwordx4 v[36:39], v203, s[58:59]
	v_lshl_or_b32 v202, v200, 10, v186
	global_load_dwordx4 v[40:43], v202, s[58:59]
	v_lshl_or_b32 v203, v200, 10, v187
	global_load_dwordx4 v[44:47], v203, s[58:59]
	v_lshl_or_b32 v202, v200, 10, v188
	global_load_dwordx4 v[48:51], v202, s[58:59]
	v_lshl_or_b32 v203, v200, 10, v189
	global_load_dwordx4 v[52:55], v203, s[58:59]
	v_lshl_or_b32 v202, v200, 10, v190
	global_load_dwordx4 v[56:59], v202, s[58:59]
	v_lshl_or_b32 v203, v200, 10, v191
	global_load_dwordx4 v[60:63], v203, s[58:59]
	s_add_i32 s13, s13, 1
	s_cmp_eq_u32 s13, s75
	s_cselect_b32 s13, 0, s13
	s_cselect_b32 s0, 1, 0
	s_add_i32 s14, s14, s0
.Lu3_loop:
	s_add_i32 s17, s16, s13
	s_lshl_b32 s17, s17, 9
	s_lshl_b32 s0, s14, 6
	s_add_i32 s17, s17, s0
	v_add_u32_e32 v249, s17, v225
	ds_read_b32 v200, v249
	s_waitcnt lgkmcnt(0)
	v_lshl_or_b32 v202, v200, 10, v176
	global_load_dwordx4 v[64:67], v202, s[58:59]
	v_lshl_or_b32 v203, v200, 10, v177
	global_load_dwordx4 v[68:71], v203, s[58:59]
	v_lshl_or_b32 v202, v200, 10, v178
	global_load_dwordx4 v[72:75], v202, s[58:59]
	v_lshl_or_b32 v203, v200, 10, v179
	global_load_dwordx4 v[76:79], v203, s[58:59]
	v_lshl_or_b32 v202, v200, 10, v180
	global_load_dwordx4 v[80:83], v202, s[58:59]
	v_lshl_or_b32 v203, v200, 10, v181
	global_load_dwordx4 v[84:87], v203, s[58:59]
	v_lshl_or_b32 v202, v200, 10, v182
	global_load_dwordx4 v[88:91], v202, s[58:59]
	v_lshl_or_b32 v203, v200, 10, v183
	global_load_dwordx4 v[92:95], v203, s[58:59]
	v_lshl_or_b32 v202, v200, 10, v184
	global_load_dwordx4 v[96:99], v202, s[58:59]
	v_lshl_or_b32 v203, v200, 10, v185
	global_load_dwordx4 v[100:103], v203, s[58:59]
	v_lshl_or_b32 v202, v200, 10, v186
	global_load_dwordx4 v[104:107], v202, s[58:59]
	v_lshl_or_b32 v203, v200, 10, v187
	global_load_dwordx4 v[108:111], v203, s[58:59]
	v_lshl_or_b32 v202, v200, 10, v188
	global_load_dwordx4 v[112:115], v202, s[58:59]
	v_lshl_or_b32 v203, v200, 10, v189
	global_load_dwordx4 v[116:119], v203, s[58:59]
	v_lshl_or_b32 v202, v200, 10, v190
	global_load_dwordx4 v[120:123], v202, s[58:59]
	v_lshl_or_b32 v203, v200, 10, v191
	global_load_dwordx4 v[124:127], v203, s[58:59]
	s_add_i32 s13, s13, 1
	s_cmp_eq_u32 s13, s75
	s_cselect_b32 s13, 0, s13
	s_cselect_b32 s0, 1, 0
	s_add_i32 s14, s14, s0
	s_add_i32 s18, s15, s19
	s_lshl_b32 s0, s18, 2
	s_add_i32 s0, s0, 0x6400
	v_mov_b32_e32 v206, s0
	ds_read_b32 v205, v206
	s_add_i32 s17, s16, s19
	s_lshl_b32 s17, s17, 9
	s_lshl_b32 s0, s20, 6
	s_add_i32 s17, s17, s0
	v_add_u32_e32 v207, s17, v225
	ds_read_b32 v208, v207 offset:16384
	s_lshl_b32 s0, s18, 10
	s_add_i32 s0, s0, 0x8000
	v_add_u32_e32 v218, s0, v176
	ds_read_b128 v[160:163], v218
	v_add_u32_e32 v219, s0, v177
	ds_read_b128 v[164:167], v219
	v_add_u32_e32 v220, s0, v178
	ds_read_b128 v[168:171], v220
	v_add_u32_e32 v221, s0, v179
	ds_read_b128 v[172:175], v221
	s_waitcnt vmcnt(31) lgkmcnt(3)
	v_mfma_f32_16x16x32_fp8_fp8 v[192:195], v[160:161], v[0:1], 0
	v_mfma_f32_16x16x32_fp8_fp8 v[192:195], v[162:163], v[2:3], v[192:195]
	v_add_u32_e32 v218, s0, v180
	ds_read_b128 v[160:163], v218
	s_waitcnt vmcnt(30) lgkmcnt(3)
	v_mfma_f32_16x16x32_fp8_fp8 v[196:199], v[164:165], v[4:5], 0
	v_mfma_f32_16x16x32_fp8_fp8 v[196:199], v[166:167], v[6:7], v[196:199]
	v_add_u32_e32 v219, s0, v181
	ds_read_b128 v[164:167], v219
	s_waitcnt vmcnt(29) lgkmcnt(3)
	v_mfma_f32_16x16x32_fp8_fp8 v[192:195], v[168:169], v[8:9], v[192:195]
	v_mfma_f32_16x16x32_fp8_fp8 v[192:195], v[170:171], v[10:11], v[192:195]
	v_add_u32_e32 v220, s0, v182
	ds_read_b128 v[168:171], v220
	s_waitcnt vmcnt(28) lgkmcnt(3)
	v_mfma_f32_16x16x32_fp8_fp8 v[196:199], v[172:173], v[12:13], v[196:199]
	v_mfma_f32_16x16x32_fp8_fp8 v[196:199], v[174:175], v[14:15], v[196:199]
	v_add_u32_e32 v221, s0, v183
	ds_read_b128 v[172:175], v221
	s_waitcnt vmcnt(27) lgkmcnt(3)
	v_mfma_f32_16x16x32_fp8_fp8 v[192:195], v[160:161], v[16:17], v[192:195]
	v_mfma_f32_16x16x32_fp8_fp8 v[192:195], v[162:163], v[18:19], v[192:195]
	v_add_u32_e32 v218, s0, v184
	ds_read_b128 v[160:163], v218
	s_waitcnt vmcnt(26) lgkmcnt(3)
	v_mfma_f32_16x16x32_fp8_fp8 v[196:199], v[164:165], v[20:21], v[196:199]
	v_mfma_f32_16x16x32_fp8_fp8 v[196:199], v[166:167], v[22:23], v[196:199]
	v_add_u32_e32 v219, s0, v185
	ds_read_b128 v[164:167], v219
	s_waitcnt vmcnt(25) lgkmcnt(3)
	v_mfma_f32_16x16x32_fp8_fp8 v[192:195], v[168:169], v[24:25], v[192:195]
	v_mfma_f32_16x16x32_fp8_fp8 v[192:195], v[170:171], v[26:27], v[192:195]
	v_add_u32_e32 v220, s0, v186
	ds_read_b128 v[168:171], v220
	s_waitcnt vmcnt(24) lgkmcnt(3)
	v_mfma_f32_16x16x32_fp8_fp8 v[196:199], v[172:173], v[28:29], v[196:199]
	v_mfma_f32_16x16x32_fp8_fp8 v[196:199], v[174:175], v[30:31], v[196:199]
	v_add_u32_e32 v221, s0, v187
	ds_read_b128 v[172:175], v221
	s_waitcnt vmcnt(23) lgkmcnt(3)
	v_mfma_f32_16x16x32_fp8_fp8 v[192:195], v[160:161], v[32:33], v[192:195]
	v_mfma_f32_16x16x32_fp8_fp8 v[192:195], v[162:163], v[34:35], v[192:195]
	v_add_u32_e32 v218, s0, v188
	ds_read_b128 v[160:163], v218
	s_waitcnt vmcnt(22) lgkmcnt(3)
	v_mfma_f32_16x16x32_fp8_fp8 v[196:199], v[164:165], v[36:37], v[196:199]
	v_mfma_f32_16x16x32_fp8_fp8 v[196:199], v[166:167], v[38:39], v[196:199]
	v_add_u32_e32 v219, s0, v189
	ds_read_b128 v[164:167], v219
	s_waitcnt vmcnt(21) lgkmcnt(3)
	v_mfma_f32_16x16x32_fp8_fp8 v[192:195], v[168:169], v[40:41], v[192:195]
	v_mfma_f32_16x16x32_fp8_fp8 v[192:195], v[170:171], v[42:43], v[192:195]
	v_add_u32_e32 v220, s0, v190
	ds_read_b128 v[168:171], v220
	s_waitcnt vmcnt(20) lgkmcnt(3)
	v_mfma_f32_16x16x32_fp8_fp8 v[196:199], v[172:173], v[44:45], v[196:199]
	v_mfma_f32_16x16x32_fp8_fp8 v[196:199], v[174:175], v[46:47], v[196:199]
	v_add_u32_e32 v221, s0, v191
	ds_read_b128 v[172:175], v221
	s_waitcnt vmcnt(19) lgkmcnt(3)
	v_mfma_f32_16x16x32_fp8_fp8 v[192:195], v[160:161], v[48:49], v[192:195]
	v_mfma_f32_16x16x32_fp8_fp8 v[192:195], v[162:163], v[50:51], v[192:195]
	s_waitcnt vmcnt(18) lgkmcnt(2)
	v_mfma_f32_16x16x32_fp8_fp8 v[196:199], v[164:165], v[52:53], v[196:199]
	v_mfma_f32_16x16x32_fp8_fp8 v[196:199], v[166:167], v[54:55], v[196:199]
	s_waitcnt vmcnt(17) lgkmcnt(1)
	v_mfma_f32_16x16x32_fp8_fp8 v[192:195], v[168:169], v[56:57], v[192:195]
	v_mfma_f32_16x16x32_fp8_fp8 v[192:195], v[170:171], v[58:59], v[192:195]
	s_waitcnt vmcnt(16) lgkmcnt(0)
	v_mfma_f32_16x16x32_fp8_fp8 v[196:199], v[172:173], v[60:61], v[196:199]
	v_mfma_f32_16x16x32_fp8_fp8 v[196:199], v[174:175], v[62:63], v[196:199]
	s_nop 7
	s_nop 3
	v_pk_add_f32 v[200:201], v[192:193], v[196:197]
	v_pk_add_f32 v[202:203], v[194:195], v[198:199]
	v_cmp_eq_u32_e32 vcc, 1, v224
	s_nop 1
	v_cndmask_b32_e32 v200, v200, v201, vcc
	v_cmp_eq_u32_e32 vcc, 2, v224
	s_nop 1
	v_cndmask_b32_e32 v200, v200, v202, vcc
	v_cmp_eq_u32_e32 vcc, 3, v224
	s_nop 1
	v_cndmask_b32_e32 v200, v200, v203, vcc
	ds_bpermute_b32 v200, v248, v200
	s_waitcnt lgkmcnt(0)
	v_mul_f32_e32 v205, v200, v205
	v_mul_f32_e32 v209, v205, v208
	v_mul_f32_e32 v205, 0x3f3504f3, v209
	v_cmp_nlt_f32_e64 s[0:1], |v205|, 1.0
	s_and_saveexec_b64 s[26:27], s[0:1]
	s_xor_b64 s[0:1], exec, s[26:27]
	s_cbranch_execz .Lu3_a_small
	s_mov_b32 s26, 0x378e98ab
	v_fma_f32 v218, |v205|, s26, v213
	s_mov_b32 s26, 0x3b7cd369
	v_fma_f32 v218, |v205|, v218, s26
	s_mov_b32 s26, 0xbcc618b2
	v_fma_f32 v218, |v205|, v218, s26
	s_mov_b32 s26, 0x3dda74e4
	v_fma_f32 v218, |v205|, v218, s26
	s_mov_b32 s26, 0x3f228afd
	v_fma_f32 v218, |v205|, v218, s26
	s_mov_b32 s26, 0x3e03c728
	v_fma_f32 v218, |v205|, v218, s26
	v_fma_f32 v218, |v205|, v218, |v205|
	v_mul_f32_e32 v219, 0xbfb8aa3b, v218
	v_fma_f32 v220, v218, s95, -v219
	v_rndne_f32_e32 v221, v219
	v_fmac_f32_e32 v220, 0xb2a5705f, v218
	v_sub_f32_e32 v219, v219, v221
	v_add_f32_e32 v219, v219, v220
	v_cvt_i32_f32_e32 v220, v221
	v_exp_f32_e32 v219, v219
	v_cmp_nlt_f32_e32 vcc, s96, v218
	v_ldexp_f32 v219, v219, v220
	s_nop 0
	v_cndmask_b32_e32 v219, 0, v219, vcc
	v_cmp_ngt_f32_e32 vcc, s97, v218
	s_nop 1
	v_cndmask_b32_e32 v218, v214, v219, vcc
	v_sub_f32_e32 v218, 1.0, v218
.Lu3_a_small:
	s_andn2_saveexec_b64 s[0:1], s[0:1]
	s_cbranch_execz .Lu3_a_join
	v_mul_f32_e32 v218, v205, v205
	v_fmamk_f32 v219, v218, 0xba1345e1, v137
	v_fmaak_f32 v219, v218, v219, 0xbcdac9b8
	v_fmaak_f32 v219, v218, v219, 0x3de703be
	v_fmaak_f32 v219, v218, v219, 0xbec09330
	v_fmaak_f32 v218, v218, v219, 0x3e0375d0
	v_fma_f32 v218, |v205|, v218, |v205|
; __device__ __forceinline__ void ph_peer(const P& p, int l, int nrows, char* smem, int dryc) {
;     ...
;         PEER_ULOAD(bA, 0);
; #pragma unroll 1
;         for (int it = 0; it < nit; it += 2) {
;           PEER_ULOAD(bB, it + 1);
;           PEER_UCOMP(bA, it);
;           if (it + 2 < nit) { PEER_ULOAD(bA, it + 2); }
.Lu3_a_join:
	s_or_b64 exec, exec, s[0:1]
	s_and_saveexec_b64 s[0:1], s[38:39]
	s_cbranch_execz .Lu3_a_done
	s_brev_b32 s26, -2
	v_bfi_b32 v205, s26, v218, v205
	v_mul_f32_e32 v209, 0.5, v209
	v_add_f32_e32 v205, 1.0, v205
	v_mul_f32_e32 v205, v209, v205
	ds_read_b32 v209, v207 offset:8192
	s_waitcnt lgkmcnt(0)
	v_mul_f32_e32 v205, v205, v209
	ds_write_b32 v207, v205 offset:8192
.Lu3_a_done:
	s_or_b64 exec, exec, s[0:1]
	s_add_i32 s19, s19, 1
	s_cmp_eq_u32 s19, s75
	s_cselect_b32 s19, 0, s19
	s_cselect_b32 s0, 1, 0
	s_add_i32 s20, s20, s0
	s_add_i32 s12, s12, 2
	s_cmp_ge_u32 s12, s76
	s_cbranch_scc1 .Lu3_last
	s_add_i32 s17, s16, s13
	s_lshl_b32 s17, s17, 9
	s_lshl_b32 s0, s14, 6
	s_add_i32 s17, s17, s0
	v_add_u32_e32 v249, s17, v225
	ds_read_b32 v200, v249
	s_waitcnt lgkmcnt(0)
	v_lshl_or_b32 v202, v200, 10, v176
	global_load_dwordx4 v[0:3], v202, s[58:59]
	v_lshl_or_b32 v203, v200, 10, v177
	global_load_dwordx4 v[4:7], v203, s[58:59]
	v_lshl_or_b32 v202, v200, 10, v178
	global_load_dwordx4 v[8:11], v202, s[58:59]
	v_lshl_or_b32 v203, v200, 10, v179
	global_load_dwordx4 v[12:15], v203, s[58:59]
	v_lshl_or_b32 v202, v200, 10, v180
	global_load_dwordx4 v[16:19], v202, s[58:59]
	v_lshl_or_b32 v203, v200, 10, v181
	global_load_dwordx4 v[20:23], v203, s[58:59]
	v_lshl_or_b32 v202, v200, 10, v182
	global_load_dwordx4 v[24:27], v202, s[58:59]
	v_lshl_or_b32 v203, v200, 10, v183
	global_load_dwordx4 v[28:31], v203, s[58:59]
	v_lshl_or_b32 v202, v200, 10, v184
	global_load_dwordx4 v[32:35], v202, s[58:59]
	v_lshl_or_b32 v203, v200, 10, v185
	global_load_dwordx4 v[36:39], v203, s[58:59]
	v_lshl_or_b32 v202, v200, 10, v186
	global_load_dwordx4 v[40:43], v202, s[58:59]
	v_lshl_or_b32 v203, v200, 10, v187
	global_load_dwordx4 v[44:47], v203, s[58:59]
	v_lshl_or_b32 v202, v200, 10, v188
	global_load_dwordx4 v[48:51], v202, s[58:59]
	v_lshl_or_b32 v203, v200, 10, v189
	global_load_dwordx4 v[52:55], v203, s[58:59]
	v_lshl_or_b32 v202, v200, 10, v190
	global_load_dwordx4 v[56:59], v202, s[58:59]
	v_lshl_or_b32 v203, v200, 10, v191
	global_load_dwordx4 v[60:63], v203, s[58:59]
	s_add_i32 s13, s13, 1
	s_cmp_eq_u32 s13, s75
	s_cselect_b32 s13, 0, s13
	s_cselect_b32 s0, 1, 0
	s_add_i32 s14, s14, s0
	s_add_i32 s18, s15, s19
	s_lshl_b32 s0, s18, 2
	s_add_i32 s0, s0, 0x6400
	v_mov_b32_e32 v206, s0
	ds_read_b32 v205, v206
	s_add_i32 s17, s16, s19
	s_lshl_b32 s17, s17, 9
	s_lshl_b32 s0, s20, 6
	s_add_i32 s17, s17, s0
	v_add_u32_e32 v207, s17, v225
	ds_read_b32 v208, v207 offset:16384
	s_lshl_b32 s0, s18, 10
	s_add_i32 s0, s0, 0x8000
	v_add_u32_e32 v218, s0, v176
	ds_read_b128 v[160:163], v218
	v_add_u32_e32 v219, s0, v177
	ds_read_b128 v[164:167], v219
	v_add_u32_e32 v220, s0, v178
	ds_read_b128 v[168:171], v220
	v_add_u32_e32 v221, s0, v179
	ds_read_b128 v[172:175], v221
	s_waitcnt vmcnt(31) lgkmcnt(3)
	v_mfma_f32_16x16x32_fp8_fp8 v[192:195], v[160:161], v[64:65], 0
	v_mfma_f32_16x16x32_fp8_fp8 v[192:195], v[162:163], v[66:67], v[192:195]
	v_add_u32_e32 v218, s0, v180
	ds_read_b128 v[160:163], v218
	s_waitcnt vmcnt(30) lgkmcnt(3)
	v_mfma_f32_16x16x32_fp8_fp8 v[196:199], v[164:165], v[68:69], 0
	v_mfma_f32_16x16x32_fp8_fp8 v[196:199], v[166:167], v[70:71], v[196:199]
	v_add_u32_e32 v219, s0, v181
	ds_read_b128 v[164:167], v219
	s_waitcnt vmcnt(29) lgkmcnt(3)
	v_mfma_f32_16x16x32_fp8_fp8 v[192:195], v[168:169], v[72:73], v[192:195]
	v_mfma_f32_16x16x32_fp8_fp8 v[192:195], v[170:171], v[74:75], v[192:195]
	v_add_u32_e32 v220, s0, v182
	ds_read_b128 v[168:171], v220
	s_waitcnt vmcnt(28) lgkmcnt(3)
	v_mfma_f32_16x16x32_fp8_fp8 v[196:199], v[172:173], v[76:77], v[196:199]
	v_mfma_f32_16x16x32_fp8_fp8 v[196:199], v[174:175], v[78:79], v[196:199]
	v_add_u32_e32 v221, s0, v183
	ds_read_b128 v[172:175], v221
	s_waitcnt vmcnt(27) lgkmcnt(3)
	v_mfma_f32_16x16x32_fp8_fp8 v[192:195], v[160:161], v[80:81], v[192:195]
	v_mfma_f32_16x16x32_fp8_fp8 v[192:195], v[162:163], v[82:83], v[192:195]
	v_add_u32_e32 v218, s0, v184
	ds_read_b128 v[160:163], v218
	s_waitcnt vmcnt(26) lgkmcnt(3)
	v_mfma_f32_16x16x32_fp8_fp8 v[196:199], v[164:165], v[84:85], v[196:199]
	v_mfma_f32_16x16x32_fp8_fp8 v[196:199], v[166:167], v[86:87], v[196:199]
	v_add_u32_e32 v219, s0, v185
	ds_read_b128 v[164:167], v219
	s_waitcnt vmcnt(25) lgkmcnt(3)
	v_mfma_f32_16x16x32_fp8_fp8 v[192:195], v[168:169], v[88:89], v[192:195]
	v_mfma_f32_16x16x32_fp8_fp8 v[192:195], v[170:171], v[90:91], v[192:195]
	v_add_u32_e32 v220, s0, v186
	ds_read_b128 v[168:171], v220
	s_waitcnt vmcnt(24) lgkmcnt(3)
	v_mfma_f32_16x16x32_fp8_fp8 v[196:199], v[172:173], v[92:93], v[196:199]
	v_mfma_f32_16x16x32_fp8_fp8 v[196:199], v[174:175], v[94:95], v[196:199]
	v_add_u32_e32 v221, s0, v187
	ds_read_b128 v[172:175], v221
	s_waitcnt vmcnt(23) lgkmcnt(3)
	v_mfma_f32_16x16x32_fp8_fp8 v[192:195], v[160:161], v[96:97], v[192:195]
	v_mfma_f32_16x16x32_fp8_fp8 v[192:195], v[162:163], v[98:99], v[192:195]
	v_add_u32_e32 v218, s0, v188
	ds_read_b128 v[160:163], v218
	s_waitcnt vmcnt(22) lgkmcnt(3)
	v_mfma_f32_16x16x32_fp8_fp8 v[196:199], v[164:165], v[100:101], v[196:199]
	v_mfma_f32_16x16x32_fp8_fp8 v[196:199], v[166:167], v[102:103], v[196:199]
	v_add_u32_e32 v219, s0, v189
	ds_read_b128 v[164:167], v219
	s_waitcnt vmcnt(21) lgkmcnt(3)
	v_mfma_f32_16x16x32_fp8_fp8 v[192:195], v[168:169], v[104:105], v[192:195]
	v_mfma_f32_16x16x32_fp8_fp8 v[192:195], v[170:171], v[106:107], v[192:195]
	v_add_u32_e32 v220, s0, v190
	ds_read_b128 v[168:171], v220
	s_waitcnt vmcnt(20) lgkmcnt(3)
	v_mfma_f32_16x16x32_fp8_fp8 v[196:199], v[172:173], v[108:109], v[196:199]
	v_mfma_f32_16x16x32_fp8_fp8 v[196:199], v[174:175], v[110:111], v[196:199]
	v_add_u32_e32 v221, s0, v191
	ds_read_b128 v[172:175], v221
	s_waitcnt vmcnt(19) lgkmcnt(3)
	v_mfma_f32_16x16x32_fp8_fp8 v[192:195], v[160:161], v[112:113], v[192:195]
	v_mfma_f32_16x16x32_fp8_fp8 v[192:195], v[162:163], v[114:115], v[192:195]
	s_waitcnt vmcnt(18) lgkmcnt(2)
	v_mfma_f32_16x16x32_fp8_fp8 v[196:199], v[164:165], v[116:117], v[196:199]
	v_mfma_f32_16x16x32_fp8_fp8 v[196:199], v[166:167], v[118:119], v[196:199]
	s_waitcnt vmcnt(17) lgkmcnt(1)
	v_mfma_f32_16x16x32_fp8_fp8 v[192:195], v[168:169], v[120:121], v[192:195]
	v_mfma_f32_16x16x32_fp8_fp8 v[192:195], v[170:171], v[122:123], v[192:195]
	s_waitcnt vmcnt(16) lgkmcnt(0)
	v_mfma_f32_16x16x32_fp8_fp8 v[196:199], v[172:173], v[124:125], v[196:199]
	v_mfma_f32_16x16x32_fp8_fp8 v[196:199], v[174:175], v[126:127], v[196:199]
	s_nop 7
	s_nop 3
	v_pk_add_f32 v[200:201], v[192:193], v[196:197]
	v_pk_add_f32 v[202:203], v[194:195], v[198:199]
	v_cmp_eq_u32_e32 vcc, 1, v224
	s_nop 1
	v_cndmask_b32_e32 v200, v200, v201, vcc
	v_cmp_eq_u32_e32 vcc, 2, v224
	s_nop 1
	v_cndmask_b32_e32 v200, v200, v202, vcc
	v_cmp_eq_u32_e32 vcc, 3, v224
	s_nop 1
	v_cndmask_b32_e32 v200, v200, v203, vcc
	ds_bpermute_b32 v200, v248, v200
	s_waitcnt lgkmcnt(0)
	v_mul_f32_e32 v205, v200, v205
	v_mul_f32_e32 v209, v205, v208
	v_mul_f32_e32 v205, 0x3f3504f3, v209
	v_cmp_nlt_f32_e64 s[0:1], |v205|, 1.0
	s_and_saveexec_b64 s[26:27], s[0:1]
	s_xor_b64 s[0:1], exec, s[26:27]
	s_cbranch_execz .Lu3_b_small
	s_mov_b32 s26, 0x378e98ab
	v_fma_f32 v218, |v205|, s26, v213
	s_mov_b32 s26, 0x3b7cd369
	v_fma_f32 v218, |v205|, v218, s26
	s_mov_b32 s26, 0xbcc618b2
	v_fma_f32 v218, |v205|, v218, s26
	s_mov_b32 s26, 0x3dda74e4
	v_fma_f32 v218, |v205|, v218, s26
	s_mov_b32 s26, 0x3f228afd
	v_fma_f32 v218, |v205|, v218, s26
	s_mov_b32 s26, 0x3e03c728
	v_fma_f32 v218, |v205|, v218, s26
	v_fma_f32 v218, |v205|, v218, |v205|
	v_mul_f32_e32 v219, 0xbfb8aa3b, v218
	v_fma_f32 v220, v218, s95, -v219
	v_rndne_f32_e32 v221, v219
	v_fmac_f32_e32 v220, 0xb2a5705f, v218
	v_sub_f32_e32 v219, v219, v221
	v_add_f32_e32 v219, v219, v220
	v_cvt_i32_f32_e32 v220, v221
	v_exp_f32_e32 v219, v219
	v_cmp_nlt_f32_e32 vcc, s96, v218
	v_ldexp_f32 v219, v219, v220
	s_nop 0
	v_cndmask_b32_e32 v219, 0, v219, vcc
	v_cmp_ngt_f32_e32 vcc, s97, v218
	s_nop 1
	v_cndmask_b32_e32 v218, v214, v219, vcc
	v_sub_f32_e32 v218, 1.0, v218

; __device__ __forceinline__ void ph_peer(const P& p, int l, int nrows, char* smem, int dryc) {
;     ...
;         for (int it = 0; it < nit; it += 2) {
;           PEER_ULOAD(bB, it + 1);
;           PEER_UCOMP(bA, it);
;           if (it + 2 < nit) { PEER_ULOAD(bA, it + 2); }
;           PEER_UCOMP(bB, it + 1);
;         }
.Lu3_b_done:
	s_or_b64 exec, exec, s[0:1]
	s_add_i32 s19, s19, 1
	s_cmp_eq_u32 s19, s75
	s_cselect_b32 s19, 0, s19
	s_cselect_b32 s0, 1, 0
	s_add_i32 s20, s20, s0
	s_branch .Lu3_loop
.Lu3_last:
	s_add_i32 s18, s15, s19
	s_lshl_b32 s0, s18, 2
	s_add_i32 s0, s0, 0x6400
	v_mov_b32_e32 v206, s0
	ds_read_b32 v205, v206
	s_add_i32 s17, s16, s19
	s_lshl_b32 s17, s17, 9
	s_lshl_b32 s0, s20, 6
	s_add_i32 s17, s17, s0
	v_add_u32_e32 v207, s17, v225
	ds_read_b32 v208, v207 offset:16384
	s_lshl_b32 s0, s18, 10
	s_add_i32 s0, s0, 0x8000
	v_add_u32_e32 v218, s0, v176
	ds_read_b128 v[160:163], v218
	v_add_u32_e32 v219, s0, v177
	ds_read_b128 v[164:167], v219
	v_add_u32_e32 v220, s0, v178
	ds_read_b128 v[168:171], v220
	v_add_u32_e32 v221, s0, v179
	ds_read_b128 v[172:175], v221
	s_waitcnt vmcnt(15) lgkmcnt(3)
	v_mfma_f32_16x16x32_fp8_fp8 v[192:195], v[160:161], v[64:65], 0
	v_mfma_f32_16x16x32_fp8_fp8 v[192:195], v[162:163], v[66:67], v[192:195]
	v_add_u32_e32 v218, s0, v180
	ds_read_b128 v[160:163], v218
	s_waitcnt vmcnt(14) lgkmcnt(3)
	v_mfma_f32_16x16x32_fp8_fp8 v[196:199], v[164:165], v[68:69], 0
	v_mfma_f32_16x16x32_fp8_fp8 v[196:199], v[166:167], v[70:71], v[196:199]
	v_add_u32_e32 v219, s0, v181
	ds_read_b128 v[164:167], v219
	s_waitcnt vmcnt(13) lgkmcnt(3)
	v_mfma_f32_16x16x32_fp8_fp8 v[192:195], v[168:169], v[72:73], v[192:195]
	v_mfma_f32_16x16x32_fp8_fp8 v[192:195], v[170:171], v[74:75], v[192:195]
	v_add_u32_e32 v220, s0, v182
	ds_read_b128 v[168:171], v220
	s_waitcnt vmcnt(12) lgkmcnt(3)
	v_mfma_f32_16x16x32_fp8_fp8 v[196:199], v[172:173], v[76:77], v[196:199]
	v_mfma_f32_16x16x32_fp8_fp8 v[196:199], v[174:175], v[78:79], v[196:199]
	v_add_u32_e32 v221, s0, v183
	ds_read_b128 v[172:175], v221
	s_waitcnt vmcnt(11) lgkmcnt(3)
	v_mfma_f32_16x16x32_fp8_fp8 v[192:195], v[160:161], v[80:81], v[192:195]
	v_mfma_f32_16x16x32_fp8_fp8 v[192:195], v[162:163], v[82:83], v[192:195]
	v_add_u32_e32 v218, s0, v184
	ds_read_b128 v[160:163], v218
	s_waitcnt vmcnt(10) lgkmcnt(3)
	v_mfma_f32_16x16x32_fp8_fp8 v[196:199], v[164:165], v[84:85], v[196:199]
	v_mfma_f32_16x16x32_fp8_fp8 v[196:199], v[166:167], v[86:87], v[196:199]
	v_add_u32_e32 v219, s0, v185
	ds_read_b128 v[164:167], v219
	s_waitcnt vmcnt(9) lgkmcnt(3)
	v_mfma_f32_16x16x32_fp8_fp8 v[192:195], v[168:169], v[88:89], v[192:195]
	v_mfma_f32_16x16x32_fp8_fp8 v[192:195], v[170:171], v[90:91], v[192:195]
	v_add_u32_e32 v220, s0, v186
	ds_read_b128 v[168:171], v220
	s_waitcnt vmcnt(8) lgkmcnt(3)
	v_mfma_f32_16x16x32_fp8_fp8 v[196:199], v[172:173], v[92:93], v[196:199]
	v_mfma_f32_16x16x32_fp8_fp8 v[196:199], v[174:175], v[94:95], v[196:199]
	v_add_u32_e32 v221, s0, v187
	ds_read_b128 v[172:175], v221
	s_waitcnt vmcnt(7) lgkmcnt(3)
	v_mfma_f32_16x16x32_fp8_fp8 v[192:195], v[160:161], v[96:97], v[192:195]
	v_mfma_f32_16x16x32_fp8_fp8 v[192:195], v[162:163], v[98:99], v[192:195]
	v_add_u32_e32 v218, s0, v188
	ds_read_b128 v[160:163], v218
	s_waitcnt vmcnt(6) lgkmcnt(3)
	v_mfma_f32_16x16x32_fp8_fp8 v[196:199], v[164:165], v[100:101], v[196:199]
	v_mfma_f32_16x16x32_fp8_fp8 v[196:199], v[166:167], v[102:103], v[196:199]
	v_add_u32_e32 v219, s0, v189
	ds_read_b128 v[164:167], v219
	s_waitcnt vmcnt(5) lgkmcnt(3)
	v_mfma_f32_16x16x32_fp8_fp8 v[192:195], v[168:169], v[104:105], v[192:195]
	v_mfma_f32_16x16x32_fp8_fp8 v[192:195], v[170:171], v[106:107], v[192:195]
	v_add_u32_e32 v220, s0, v190
	ds_read_b128 v[168:171], v220
	s_waitcnt vmcnt(4) lgkmcnt(3)
	v_mfma_f32_16x16x32_fp8_fp8 v[196:199], v[172:173], v[108:109], v[196:199]
	v_mfma_f32_16x16x32_fp8_fp8 v[196:199], v[174:175], v[110:111], v[196:199]
	v_add_u32_e32 v221, s0, v191
	ds_read_b128 v[172:175], v221
	s_waitcnt vmcnt(3) lgkmcnt(3)
	v_mfma_f32_16x16x32_fp8_fp8 v[192:195], v[160:161], v[112:113], v[192:195]
	v_mfma_f32_16x16x32_fp8_fp8 v[192:195], v[162:163], v[114:115], v[192:195]
	s_waitcnt vmcnt(2) lgkmcnt(2)
	v_mfma_f32_16x16x32_fp8_fp8 v[196:199], v[164:165], v[116:117], v[196:199]
	v_mfma_f32_16x16x32_fp8_fp8 v[196:199], v[166:167], v[118:119], v[196:199]
	s_waitcnt vmcnt(1) lgkmcnt(1)
	v_mfma_f32_16x16x32_fp8_fp8 v[192:195], v[168:169], v[120:121], v[192:195]
	v_mfma_f32_16x16x32_fp8_fp8 v[192:195], v[170:171], v[122:123], v[192:195]
	s_waitcnt vmcnt(0) lgkmcnt(0)
	v_mfma_f32_16x16x32_fp8_fp8 v[196:199], v[172:173], v[124:125], v[196:199]
	v_mfma_f32_16x16x32_fp8_fp8 v[196:199], v[174:175], v[126:127], v[196:199]
	s_nop 7
	s_nop 3
	v_pk_add_f32 v[200:201], v[192:193], v[196:197]
	v_pk_add_f32 v[202:203], v[194:195], v[198:199]
	v_cmp_eq_u32_e32 vcc, 1, v224
	s_nop 1
	v_cndmask_b32_e32 v200, v200, v201, vcc
	v_cmp_eq_u32_e32 vcc, 2, v224
	s_nop 1
	v_cndmask_b32_e32 v200, v200, v202, vcc
	v_cmp_eq_u32_e32 vcc, 3, v224
	s_nop 1
	v_cndmask_b32_e32 v200, v200, v203, vcc
	ds_bpermute_b32 v200, v248, v200
	s_waitcnt lgkmcnt(0)
	v_mul_f32_e32 v205, v200, v205
	v_mul_f32_e32 v209, v205, v208
	v_mul_f32_e32 v205, 0x3f3504f3, v209
	v_cmp_nlt_f32_e64 s[0:1], |v205|, 1.0
	s_and_saveexec_b64 s[26:27], s[0:1]
	s_xor_b64 s[0:1], exec, s[26:27]
	s_cbranch_execz .Lu3_c_small
	s_mov_b32 s26, 0x378e98ab
	v_fma_f32 v218, |v205|, s26, v213
	s_mov_b32 s26, 0x3b7cd369
	v_fma_f32 v218, |v205|, v218, s26
	s_mov_b32 s26, 0xbcc618b2
	v_fma_f32 v218, |v205|, v218, s26
	s_mov_b32 s26, 0x3dda74e4
	v_fma_f32 v218, |v205|, v218, s26
	s_mov_b32 s26, 0x3f228afd
	v_fma_f32 v218, |v205|, v218, s26
	s_mov_b32 s26, 0x3e03c728
	v_fma_f32 v218, |v205|, v218, s26
	v_fma_f32 v218, |v205|, v218, |v205|
	v_mul_f32_e32 v219, 0xbfb8aa3b, v218
	v_fma_f32 v220, v218, s95, -v219
	v_rndne_f32_e32 v221, v219
	v_fmac_f32_e32 v220, 0xb2a5705f, v218
	v_sub_f32_e32 v219, v219, v221
	v_add_f32_e32 v219, v219, v220
	v_cvt_i32_f32_e32 v220, v221
	v_exp_f32_e32 v219, v219
	v_cmp_nlt_f32_e32 vcc, s96, v218
	v_ldexp_f32 v219, v219, v220
	s_nop 0
	v_cndmask_b32_e32 v219, 0, v219, vcc
	v_cmp_ngt_f32_e32 vcc, s97, v218
	s_nop 1
	v_cndmask_b32_e32 v218, v214, v219, vcc
	v_sub_f32_e32 v218, 1.0, v218

; __device__ __forceinline__ void ph_peer(const P& p, int l, int nrows, char* smem, int dryc) {
;     ...
;         PEER_ULOAD(bA, 0);
; #pragma unroll 1
;         for (int it = 0; it < nit; it += 2) {
;           PEER_ULOAD(bB, it + 1);
;           PEER_UCOMP(bA, it);
;           if (it + 2 < nit) { PEER_ULOAD(bA, it + 2); }
;           PEER_UCOMP(bB, it + 1);
;         }
.Lu3_c_done:
	s_or_b64 exec, exec, s[0:1]
	s_add_i32 s19, s19, 1
	s_cmp_eq_u32 s19, s75
	s_cselect_b32 s19, 0, s19
	s_cselect_b32 s0, 1, 0
	s_add_i32 s20, s20, s0

; __device__ __forceinline__ void ph_peer(const P& p, int l, int nrows, char* smem, int dryc) {
;     ...
;           const float* m = MOD + (size_t)(l * 9 + modrow_of(row)) * 6144;
;           float tt[16];
;           float* xr = xc + (size_t)row * 1024;
; #pragma unroll
;           for (int q = 0; q < 4; q++) {
;             int c = lane * 16 + q * 4;
;             float4 x4 = *(const float4*)(xr + c); float4 g5 = *(const float4*)(m + 5 * 1024 + c);
;             tt[q * 4 + 0] = ALPHA * x4.x + g5.x * f[q * 4 + 0];
;             tt[q * 4 + 1] = ALPHA * x4.y + g5.y * f[q * 4 + 1];
;             tt[q * 4 + 2] = ALPHA * x4.z + g5.z * f[q * 4 + 2];
;             tt[q * 4 + 3] = ALPHA * x4.w + g5.w * f[q * 4 + 3];
;           }
;           float sm = 0.f;
; #pragma unroll
;           for (int i = 0; i < 16; i++) sm += tt[i];
;           float mean = wave_sum(sm) * (1.f / 1024.f);
;           float ss = 0.f;
; #pragma unroll
;           for (int i = 0; i < 16; i++) { float dd = tt[i] - mean; ss += dd * dd; }
;           float rinv = rsqrtf(wave_sum(ss) * (1.f / 1024.f) + 1e-5f);
.LBB0_751:
	s_and_b64 vcc, exec, s[12:13]
	s_cbranch_vccnz .LBB0_719
	v_add_u32_e32 v66, s19, v248
	s_waitcnt vmcnt(15)
	v_min_i32_e32 v0, 0x4000, v66
	s_waitcnt vmcnt(5)
	v_ashrrev_i32_e32 v38, 11, v0
	v_add_u32_e32 v0, s77, v38
	v_mul_hi_i32_i24_e32 v1, 0x6000, v0
	v_mul_i32_i24_e32 v0, 0x6000, v0
	v_lshl_add_u64 v[0:1], s[2:3], 0, v[0:1]
	v_lshl_add_u64 v[4:5], v[0:1], 0, v[132:133]
	s_mov_b64 s[0:1], 0x5000
	s_waitcnt vmcnt(2)
	v_lshl_add_u64 v[12:13], v[4:5], 0, s[0:1]
	s_movk_i32 s0, 0x5000
	v_ashrrev_i32_e32 v67, 31, v66
	v_add_co_u32_e32 v8, vcc, s0, v4
	v_lshlrev_b64 v[16:17], 12, v[66:67]
	s_nop 0
	v_addc_co_u32_e32 v9, vcc, 0, v5, vcc
	v_lshl_add_u64 v[64:65], v[150:151], 0, v[16:17]
	global_load_dwordx4 v[0:3], v[12:13], off offset:48
	global_load_dwordx4 v[4:7], v[12:13], off offset:32
	s_nop 0
	global_load_dwordx4 v[8:11], v[8:9], off
	s_nop 0
	global_load_dwordx4 v[12:15], v[12:13], off offset:16
	s_nop 0
	global_load_dwordx4 v[16:19], v[64:65], off offset:48
	global_load_dwordx4 v[20:23], v[64:65], off offset:32
	global_load_dwordx4 v[24:27], v[64:65], off offset:16
	global_load_dwordx4 v[28:31], v[64:65], off
	s_mov_b32 s0, 0x3fd744fd
	v_mov_b64_e32 v[36:37], s[2:3]
	s_waitcnt vmcnt(6)
	v_pk_mul_f32 v[4:5], v[182:183], v[4:5]
	s_waitcnt vmcnt(5)
	v_pk_mul_f32 v[8:9], v[174:175], v[8:9]
	v_pk_mul_f32 v[0:1], v[186:187], v[0:1]
	s_waitcnt vmcnt(0)
	v_pk_fma_f32 v[80:81], v[28:29], s[0:1], v[8:9] op_sel_hi:[1,0,1]
	v_pk_mul_f32 v[10:11], v[172:173], v[10:11]
	v_pk_fma_f32 v[68:69], v[16:17], s[0:1], v[0:1] op_sel_hi:[1,0,1]
	v_add_f32_e32 v0, 0, v80
	v_pk_fma_f32 v[82:83], v[30:31], s[0:1], v[10:11] op_sel_hi:[1,0,1]
	v_add_f32_e32 v0, v0, v81
	v_pk_mul_f32 v[12:13], v[180:181], v[12:13]
	v_add_f32_e32 v0, v0, v82
	v_pk_fma_f32 v[76:77], v[24:25], s[0:1], v[12:13] op_sel_hi:[1,0,1]
	v_add_f32_e32 v0, v0, v83
	v_pk_mul_f32 v[14:15], v[176:177], v[14:15]
	v_add_f32_e32 v0, v0, v76
	v_pk_fma_f32 v[78:79], v[26:27], s[0:1], v[14:15] op_sel_hi:[1,0,1]
	v_add_f32_e32 v0, v0, v77
	v_add_f32_e32 v0, v0, v78
	v_pk_fma_f32 v[72:73], v[20:21], s[0:1], v[4:5] op_sel_hi:[1,0,1]
	v_add_f32_e32 v0, v0, v79
	v_pk_mul_f32 v[6:7], v[178:179], v[6:7]
	v_add_f32_e32 v0, v0, v72
	v_pk_fma_f32 v[74:75], v[22:23], s[0:1], v[6:7] op_sel_hi:[1,0,1]
	v_add_f32_e32 v0, v0, v73
	v_add_f32_e32 v0, v0, v74
	v_add_f32_e32 v0, v0, v75
	v_pk_mul_f32 v[2:3], v[184:185], v[2:3]
	v_add_f32_e32 v0, v0, v68
	v_pk_fma_f32 v[70:71], v[18:19], s[0:1], v[2:3] op_sel_hi:[1,0,1]
	v_add_f32_e32 v0, v0, v69
	v_add_f32_e32 v0, v0, v70
	v_add_f32_e32 v4, v0, v71
	s_movk_i32 s0, 0x6000
	global_load_dwordx4 v[0:3], v[146:147], off offset:48
	global_load_dwordx4 v[16:19], v[146:147], off offset:32
	global_load_dwordx4 v[32:35], v[146:147], off offset:16
	global_load_dwordx4 v[48:51], v[146:147], off
	global_load_dwordx4 v[8:11], v[148:149], off offset:48
	global_load_dwordx4 v[24:27], v[148:149], off offset:32
	global_load_dwordx4 v[40:43], v[148:149], off offset:16
	global_load_dwordx4 v[56:59], v[148:149], off
	s_nop 1
	v_add_f32_dpp v4, v4, v4 quad_perm:[1,0,3,2] row_mask:0xf bank_mask:0xf
	s_nop 1
	v_add_f32_dpp v6, v4, v4 quad_perm:[2,3,0,1] row_mask:0xf bank_mask:0xf
	v_add_u32_e32 v4, s78, v38
	v_mad_i64_i32 v[4:5], s[0:1], v4, s0, v[36:37]
	v_lshl_add_u64 v[12:13], v[4:5], 0, v[132:133]
	s_nop 1
	v_add_f32_dpp v14, v6, v6 row_half_mirror row_mask:0xf bank_mask:0xf
	s_mov_b64 s[0:1], 0x1000
	v_lshl_add_u64 v[44:45], v[12:13], 0, s[0:1]
	s_movk_i32 s0, 0x1000
	global_load_dwordx4 v[4:7], v[12:13], off offset:48
	global_load_dwordx4 v[20:23], v[12:13], off offset:32
	global_load_dwordx4 v[36:39], v[12:13], off offset:16
	global_load_dwordx4 v[52:55], v[12:13], off
	s_nop 1
	v_add_f32_dpp v14, v14, v14 row_mirror row_mask:0xf bank_mask:0xf
	v_add_co_u32_e32 v12, vcc, s0, v12
	s_mov_b32 s0, 0x800000
	s_nop 0
	v_addc_co_u32_e32 v13, vcc, 0, v13, vcc
	v_mov_b32_e32 v15, v14
	v_mov_b32_e32 v84, v14
	s_nop 1
	v_permlane16_swap_b32_e32 v84, v15
	v_add_f32_e32 v84, v84, v15
	global_load_dwordx4 v[60:63], v[12:13], off
	s_nop 0
	global_load_dwordx4 v[12:15], v[44:45], off offset:48
	global_load_dwordx4 v[28:31], v[44:45], off offset:32
	s_nop 0
	global_load_dwordx4 v[44:47], v[44:45], off offset:16
	v_mov_b32_e32 v85, v84
	s_nop 1
	v_permlane32_swap_b32_e32 v84, v85
	v_add_f32_e32 v84, v84, v85
	v_mul_f32_e32 v88, 0x3a800000, v84
	v_pk_add_f32 v[84:85], v[80:81], v[88:89] op_sel_hi:[1,0] neg_lo:[0,1] neg_hi:[0,1]
	v_pk_add_f32 v[86:87], v[82:83], v[88:89] op_sel_hi:[1,0] neg_lo:[0,1] neg_hi:[0,1]
	v_pk_add_f32 v[80:81], v[78:79], v[88:89] op_sel_hi:[1,0] neg_lo:[0,1] neg_hi:[0,1]
	v_pk_add_f32 v[78:79], v[72:73], v[88:89] op_sel_hi:[1,0] neg_lo:[0,1] neg_hi:[0,1]
	v_pk_add_f32 v[72:73], v[68:69], v[88:89] op_sel_hi:[1,0] neg_lo:[0,1] neg_hi:[0,1]
	v_pk_mul_f32 v[68:69], v[84:85], v[84:85]
	v_pk_add_f32 v[82:83], v[76:77], v[88:89] op_sel_hi:[1,0] neg_lo:[0,1] neg_hi:[0,1]
	v_pk_add_f32 v[76:77], v[74:75], v[88:89] op_sel_hi:[1,0] neg_lo:[0,1] neg_hi:[0,1]
	v_pk_mul_f32 v[74:75], v[86:87], v[86:87]
	v_add_f32_e32 v68, v68, v69
	v_add_f32_e32 v68, v74, v68
	v_pk_add_f32 v[70:71], v[70:71], v[88:89] op_sel_hi:[1,0] neg_lo:[0,1] neg_hi:[0,1]
	v_pk_mul_f32 v[88:89], v[82:83], v[82:83]
	v_add_f32_e32 v68, v75, v68
	v_add_f32_e32 v68, v88, v68
	v_pk_mul_f32 v[90:91], v[80:81], v[80:81]
	v_add_f32_e32 v68, v89, v68
	v_add_f32_e32 v68, v90, v68
	v_pk_mul_f32 v[92:93], v[78:79], v[78:79]
	v_add_f32_e32 v68, v91, v68
	v_add_f32_e32 v68, v92, v68
	v_pk_mul_f32 v[94:95], v[76:77], v[76:77]
	v_add_f32_e32 v68, v93, v68
	v_add_f32_e32 v68, v94, v68
	v_pk_mul_f32 v[96:97], v[72:73], v[72:73]
	v_add_f32_e32 v68, v95, v68
	v_add_f32_e32 v68, v96, v68
	v_pk_mul_f32 v[98:99], v[70:71], v[70:71]
	v_add_f32_e32 v68, v97, v68
	v_add_f32_e32 v68, v98, v68
	v_add_f32_e32 v68, v99, v68
	s_nop 1
	v_add_f32_dpp v68, v68, v68 quad_perm:[1,0,3,2] row_mask:0xf bank_mask:0xf
	s_nop 1
	v_add_f32_dpp v68, v68, v68 quad_perm:[2,3,0,1] row_mask:0xf bank_mask:0xf
	s_nop 1
	v_add_f32_dpp v68, v68, v68 row_half_mirror row_mask:0xf bank_mask:0xf
	s_nop 1
	v_add_f32_dpp v68, v68, v68 row_mirror row_mask:0xf bank_mask:0xf
	v_mov_b32_e32 v69, v68
	s_nop 1
	v_permlane16_swap_b32_e32 v68, v69
	v_add_f32_e32 v68, v68, v69
	v_mov_b32_e32 v69, v68
	s_nop 1
	v_permlane32_swap_b32_e32 v68, v69
	v_add_f32_e32 v68, v68, v69
	v_fmamk_f32 v68, v68, 0x3a800000, v139
	v_mul_f32_e32 v69, 0x4b800000, v68
	v_cmp_gt_f32_e32 vcc, s0, v68
	s_nop 1
	v_cndmask_b32_e32 v68, v68, v69, vcc
	v_rsq_f32_e32 v74, v68
	v_lshlrev_b64 v[68:69], 10, v[66:67]
	v_lshlrev_b64 v[66:67], 11, v[66:67]
	v_lshl_add_u64 v[66:67], s[56:57], 0, v[66:67]
	v_mul_f32_e32 v75, 0x45800000, v74
	v_cndmask_b32_e32 v74, v74, v75, vcc
	s_and_b64 vcc, exec, s[14:15]
	v_mov_b32_e32 v75, v74
	s_cbranch_vccnz .LBB0_761
; __device__ __forceinline__ void ph_peer(const P& p, int l, int nrows, char* smem, int dryc) {
;     ...
; #pragma unroll
;           for (int q = 0; q < 4; q++) {
;             int c = lane * 16 + q * 4;
;             float4 y;
;             y.x = (tt[q * 4 + 0] - mean) * rinv * gg4[q][0] + bb4[q][0];
;             y.y = (tt[q * 4 + 1] - mean) * rinv * gg4[q][1] + bb4[q][1];
;             y.z = (tt[q * 4 + 2] - mean) * rinv * gg4[q][2] + bb4[q][2];
;             y.w = (tt[q * 4 + 3] - mean) * rinv * gg4[q][3] + bb4[q][3];
;             if (dry) {
;             } else if (l == 3) {
;               *(float4*)(p.out + (size_t)row * 1024 + c) = y;
;             } else {
;               *(float4*)(xr + c) = y;
;               uint2 o; o.x = pack2(y.x * (1.f + sc4[q][0]) + sh4[q][0], y.y * (1.f + sc4[q][1]) + sh4[q][1]);
;               o.y = pack2(y.z * (1.f + sc4[q][2]) + sh4[q][2], y.w * (1.f + sc4[q][3]) + sh4[q][3]);
;               *(uint2*)(xm + (size_t)row * 1024 + c) = o;
;             }
	v_pk_mul_f32 v[84:85], v[84:85], v[74:75]
	s_andn2_b64 vcc, exec, s[66:67]
	s_waitcnt vmcnt(8)
	v_pk_fma_f32 v[48:49], v[48:49], v[84:85], v[56:57]
	v_pk_mul_f32 v[56:57], v[86:87], v[74:75]
	s_mov_b64 s[0:1], -1
	v_pk_fma_f32 v[50:51], v[50:51], v[56:57], v[58:59]
	v_cndmask_b32_e64 v56, 0, 1, s[66:67]
	v_cmp_ne_u32_e64 s[12:13], 1, v56
	s_cbranch_vccnz .LBB0_755
	s_waitcnt vmcnt(3)
	v_pk_add_f32 v[56:57], v[60:61], 1.0 op_sel_hi:[1,0]
	s_mov_b64 s[0:1], 0
	v_pk_fma_f32 v[52:53], v[56:57], v[48:49], v[52:53]
	v_pk_add_f32 v[56:57], v[62:63], 1.0 op_sel_hi:[1,0]
	v_cvt_pk_bf16_f32 v52, v52, v53
	v_pk_fma_f32 v[54:55], v[56:57], v[50:51], v[54:55]
	global_store_dwordx4 v[64:65], v[48:51], off
	v_cvt_pk_bf16_f32 v53, v54, v55
	v_lshlrev_b32_e32 v54, 1, v144
	v_mov_b32_e32 v55, v133
	v_lshl_add_u64 v[54:55], v[66:67], 0, v[54:55]
	global_store_dwordx2 v[54:55], v[52:53], off
